# v16 + layer-1 pp tile moved from the out-proj phase into the barrier after attention (between arrive and wait): hides that barrier's latency
# speedup vs baseline: 1.0051x; 1.0051x over previous
; #define PG8_STAGE(bufoff, gbase, voff) do { _Pragma("unroll") for (int _i = 0; _i < 2; ++_i) \
;         __builtin_amdgcn_global_load_lds((const unsigned*)((const char*)(gbase) + (voff)[_i]), (LAS unsigned*)(lds + (bufoff) + ldsw + _i * 8192), 16, 0, 0); } while (0)
; #define PG8_WAIT_V(n) asm volatile("s_waitcnt vmcnt(" #n ")" ::: "memory")
; #define PG8_BAR __builtin_amdgcn_s_barrier()
; template <class Epi, bool ALIGN_EPI = false, bool SP2 = true>
; __device__ __forceinline__ void gemm_phase(LAS unsigned char* lds, const Gemm g, const StaticOrder& S, const Epi& E) {
;     ...
;         PG8_WAIT_V(2); PG8_BAR;
;         PG8_STAGE(PG8_SB(1, 0), cB + kstep, voffB); PG8_STAGE(PG8_SA(1, 0), cA + kstep, voffA); PG8_STAGE(PG8_SB(1, 1), cB + hstep + kstep, voffB);
;         PG8_WAIT_V(6); PG8_BAR;
;     ...
;         const bool has_next = S.next(ui + 1, nxt);
;         const char* nA = has_next ? (const char*)g.A + (size_t)nxt.pm * tstep : cA; const char* nB = has_next ? (const char*)g.Bt + (size_t)(nxt.pn + (nxt.pm >= g.bsplit ? g.badd : 0)) * tstep : cB;
.LBB0_299:
	s_lshl_b32 s0, s0, 5
	s_and_b32 s18, s0, 0x60
	s_mov_b64 s[0:1], 0x80
	s_add_i32 m0, s37, 0x18000
	v_lshl_add_u64 v[6:7], v[6:7], 0, s[0:1]
	s_lshl_b32 s5, s4, 13
	s_lshl_b32 s19, s18, 7
	s_waitcnt vmcnt(2)
	s_barrier
	global_load_lds_dwordx4 v[6:7], off
	v_lshl_add_u64 v[4:5], v[4:5], 0, s[0:1]
	s_add_i32 m0, s37, 0x1a000
	s_add_i32 s75, s37, 0x8000
	s_add_i32 s76, s37, 0xa000
	global_load_lds_dwordx4 v[4:5], off
	v_lshl_add_u64 v[2:3], v[2:3], 0, s[0:1]
	s_mov_b32 m0, s75
	s_add_u32 s6, s62, 0x10080
	global_load_lds_dwordx4 v[2:3], off
	v_lshl_add_u64 v[0:1], v[0:1], 0, s[0:1]
	s_mov_b32 m0, s76
	s_addc_u32 s7, s63, 0
	global_load_lds_dwordx4 v[0:1], off
	s_add_i32 m0, s37, 0x1c000
	v_lshl_add_u64 v[0:1], s[6:7], 0, v[42:43]
	global_load_lds_dwordx4 v[0:1], off
	v_lshl_add_u64 v[0:1], s[6:7], 0, v[46:47]
	s_add_i32 m0, s37, 0x1e000
	v_lshlrev_b32_e32 v2, 2, v149
	global_load_lds_dwordx4 v[0:1], off
	v_lshlrev_b32_e32 v0, 1, v148
	v_lshl_or_b32 v1, v149, 6, v0
	v_and_b32_e32 v2, 32, v2
	v_or_b32_e32 v0, v0, v60
	s_waitcnt vmcnt(6)
	v_bitop3_b32 v1, v1, s5, v2 bitop3:0xde
	v_bitop3_b32 v68, s19, v0, v61 bitop3:0xf6
	s_add_i32 s83, 0, 0x10000
	s_add_i32 s80, 0, 0x14000
	v_lshl_or_b32 v67, s4, 6, v149
	s_ashr_i32 s77, s34, 31
	s_mov_b32 s78, s34
	v_or_b32_e32 v69, s18, v148
	s_add_i32 s79, s2, s34
	v_mov_b64_e32 v[48:49], 0x200
	v_mov_b64_e32 v[50:51], 0x1ff
	v_add_u32_e32 v70, s83, v68
	v_add_u32_e32 v71, s80, v68
	v_add_u32_e32 v72, 0, v1
	s_add_i32 s81, s37, 0xc000
	s_add_i32 s82, s37, 0xe000
	s_mov_b64 s[6:7], 0x100
	s_mov_b64 s[18:19], 0x180
	s_add_i32 s83, s83, s69
	s_mov_b64 s[22:23], s[2:3]
	s_add_u32 s22, s22, 0x100
	s_barrier
	s_branch .LBB0_302

; template <class Epi, bool ALIGN_EPI = false, bool SP2 = true>
; __device__ __forceinline__ void gemm_phase(LAS unsigned char* lds, const Gemm g, const StaticOrder& S, const Epi& E) {
;     const int tid = threadIdx.x, wid = __builtin_amdgcn_readfirstlane(tid >> 6), lane = tid & 63, wr = wid >> 2, wc = wid & 3, fr = lane & 15, fq = lane >> 4;
;     const int K = g.K, nt = K / BK;
;     unsigned voffA[2], voffB[2];
; #pragma unroll
;     for (int i = 0; i < 2; ++i) { int R, C; stage_rc(tid * 16 + i * 8192, R, C); const int Rb = (R & ~31) + perm32(R & 31);
;         voffA[i] = (unsigned)(R * K + C) * 2u; voffB[i] = (unsigned)(Rb * K + C) * 2u; }
;     const size_t kstep = (size_t)(BK * 2);
;     const size_t hstep = (size_t)HALF * K * 2;
;     const size_t tstep = 2 * hstep;
;     const unsigned ldsw = (unsigned)wid * 1024u;
;     const int aoff = lds_byte(wr * 64 + fr, fq * 8), boff = lds_byte(wc * 32 + fr, fq * 8);
;     ...
;     if (!S.next(0, cur)) return;
.Lpp1_join:
	s_or_b64 exec, exec, s[4:5]
	s_mov_b64 s[100:101], s[0:1]
	s_add_u32 s58, s40, 0x3000000
	s_addc_u32 s59, s41, 0
	s_add_u32 s8, s40, 0x8800000
	s_addc_u32 s9, s41, 0
	s_waitcnt vmcnt(0)
	v_lshlrev_b32_e32 v0, 4, v164
	v_and_b32_e32 v1, 32, v164
	v_bitop3_b32 v56, v0, v1, 48 bitop3:0x6c
	v_lshrrev_b32_e32 v1, 5, v164
	v_lshrrev_b32_e32 v3, 1, v164
	v_and_b32_e32 v1, 4, v1
	v_bfe_u32 v2, v164, 2, 2
	v_and_b32_e32 v148, 24, v3
	v_bfe_u32 v58, v164, 2, 4
	v_or3_b32 v1, v1, v2, v148
	v_lshrrev_b32_e32 v2, 3, v164
	s_movk_i32 s0, 0x70
	v_and_or_b32 v63, v2, s0, v58
	s_movk_i32 s0, 0x60
	v_add_u32_e32 v59, 0x2000, v0
	v_and_or_b32 v64, v2, s0, v1
	v_lshrrev_b32_e32 v0, 7, v59
	s_movk_i32 s0, 0xf0
	v_and_or_b32 v65, v0, s0, v58
	s_movk_i32 s0, 0xe0
	v_and_or_b32 v66, v0, s0, v1
	v_lshlrev_b32_e32 v0, 6, v164
	v_and_b32_e32 v57, 64, v164
	v_and_b32_e32 v60, 0x3c0, v0
	v_lshlrev_b32_e32 v0, 2, v164
	v_readfirstlane_b32 s68, v164
	v_or_b32_e32 v62, v56, v57
	v_and_b32_e32 v149, 15, v164
	s_cmpk_gt_i32 s2, 0x1ff
	v_and_b32_e32 v61, 32, v0
	s_cbranch_scc1 .Lpp1_exit
	s_ashr_i32 s3, s2, 31
	s_lshr_b32 s0, s3, 29
	s_add_i32 s4, s2, s0
	s_and_b32 s0, s4, -8
	s_sub_i32 s6, s2, s0
	s_cmp_gt_i32 s6, -1
	s_cbranch_scc0 .Lpp1_295
	s_lshl_b32 s5, s6, 6
	s_cbranch_execz .Lpp1_296
	s_branch .Lpp1_297

; #define PG8_STAGE(bufoff, gbase, voff) do { _Pragma("unroll") for (int _i = 0; _i < 2; ++_i) \
;         __builtin_amdgcn_global_load_lds((const unsigned*)((const char*)(gbase) + (voff)[_i]), (LAS unsigned*)(lds + (bufoff) + ldsw + _i * 8192), 16, 0, 0); } while (0)
; #define PG8_WAIT_V(n) asm volatile("s_waitcnt vmcnt(" #n ")" ::: "memory")
; #define PG8_BAR __builtin_amdgcn_s_barrier()
; __device__ __forceinline__ unsigned xb_ld(unsigned* p)              { return __hip_atomic_load(p, __ATOMIC_RELAXED, __HIP_MEMORY_SCOPE_AGENT); }
; template <class Epi, bool ALIGN_EPI = false, bool SP2 = true>
; __device__ __forceinline__ void gemm_phase(LAS unsigned char* lds, const Gemm g, const StaticOrder& S, const Epi& E) {
;     ...
;     const char* cA = (const char*)g.A + (size_t)cur.pm * tstep; const char* cB = (const char*)g.Bt + (size_t)(cur.pn + (cur.pm >= g.bsplit ? g.badd : 0)) * tstep;
;     if constexpr (SP2) {
;         PG8_STAGE(PG8_SB(0, 0), cB, voffB); PG8_STAGE(PG8_SB(0, 1), cB + hstep, voffB); PG8_STAGE(PG8_SA(0, 0), cA, voffA); PG8_STAGE(PG8_SA(0, 1), cA + hstep, voffA);
;         if (wr == 1) PG8_BAR;
;         PG8_WAIT_V(2); PG8_BAR;
;         PG8_STAGE(PG8_SB(1, 0), cB + kstep, voffB); PG8_STAGE(PG8_SA(1, 0), cA + kstep, voffA); PG8_STAGE(PG8_SB(1, 1), cB + hstep + kstep, voffB);
;         PG8_WAIT_V(6); PG8_BAR;
; __device__ __forceinline__ void xcd_barrier(const XcdBarrier& b) {
;     asm volatile("s_waitcnt vmcnt(0)" ::: "memory");
;     __syncthreads();
;     if (threadIdx.x == 0) {
;         unsigned* bar = b.bar;
;         __builtin_amdgcn_s_waitcnt(0);
;         unsigned nloc = b.st[0], nx = b.st[1];
;         if (nloc == 0u) { xcd_barrier_complete(bar, b.x, nloc, nx); b.st[0] = nloc; b.st[1] = nx; }
;         const unsigned old = xb_add(&bar[XB_XSUB(b.x)], 1u);
;         const unsigned gen = old / nloc;
;         if (old + 1u == (gen + 1u) * nloc) {
;             __builtin_amdgcn_fence(__ATOMIC_RELEASE, "agent");
;             asm volatile("s_waitcnt vmcnt(0)" ::: "memory");
;             const unsigned og = xb_add(&bar[XB_TOP], 1u);
;             const unsigned tg = og / nx;
;             if (og + 1u == (tg + 1u) * nx) xb_add(&bar[XB_TOPGEN], 1u);
;             else XB_SPIN(xb_ld(&bar[XB_TOPGEN]) == tg, bar);
;             __builtin_amdgcn_fence(__ATOMIC_ACQUIRE, "agent");
;             xb_add(&bar[XB_XGEN(b.x)], 1u);
.Lpp1_297:
	s_lshr_b32 s0, s68, 6
	s_ashr_i32 s1, s4, 3
	s_lshr_b32 s4, s68, 8
	s_lshl_b32 s69, s0, 10
	s_add_u32 s70, s40, 0x3200000
	s_addc_u32 s71, s41, 0
	s_add_i32 s1, s5, s1
	s_ashr_i32 s5, s1, 31
	s_lshr_b32 s5, s5, 27
	s_add_i32 s5, s1, s5
	s_ashr_i32 s6, s5, 5
	s_andn2_b32 s5, s5, 31
	s_sub_i32 s1, s1, s5
	s_bfe_i32 s5, s1, 0x80000
	s_bfe_u32 s5, s5, 0x2000d
	s_add_i32 s5, s1, s5
	s_bfe_i32 s7, s5, 0x80000
	s_and_b32 s5, s5, 0xfc
	s_sub_i32 s1, s1, s5
	s_lshl_b32 s6, s6, 2
	s_sext_i32_i8 s1, s1
	s_add_i32 s36, s6, s1
	s_and_b32 s36, s2, 7
	s_lshl_b32 s36, s36, 2
	s_bfe_u32 s1, s2, 0x20003
	s_or_b32 s36, s36, s1
	s_add_i32 s36, s36, 32
	s_sext_i32_i16 s7, s7
	s_ashr_i32 s37, s36, 31
	s_ashr_i32 s84, s7, 2
	s_lshr_b32 s84, s2, 5
	s_lshl_b64 s[6:7], s[36:37], 17
	s_cmp_gt_i32 s36, 31
	s_cselect_b32 s1, 8, 0
	s_add_i32 s18, s1, s84
	s_ashr_i32 s19, s18, 31
	s_lshl_b64 s[18:19], s[18:19], 17
	s_add_u32 s62, s58, s18
	s_addc_u32 s63, s59, s19
	s_add_i32 s37, s69, 0
	v_lshl_or_b32 v42, v64, 9, v62
	s_add_i32 m0, s37, 0x10000
	v_lshl_or_b32 v46, v66, 9, v62
	global_load_lds_dwordx4 v42, s[62:63]
	s_add_i32 m0, s37, 0x12000
	s_add_u32 s18, s62, 0x10000
	global_load_lds_dwordx4 v46, s[62:63]
	s_addc_u32 s19, s63, 0
	s_add_i32 m0, s37, 0x14000
	v_lshl_or_b32 v40, v63, 9, v62
	global_load_lds_dwordx4 v42, s[18:19]
	s_add_i32 m0, s37, 0x16000
	s_add_u32 s60, s70, s6
	s_addc_u32 s61, s71, s7
	s_add_i32 s72, s37, 0x2000
	global_load_lds_dwordx4 v46, s[18:19]
	s_mov_b32 m0, s37
	s_add_u32 s6, s60, 0x10000
	v_lshl_or_b32 v44, v65, 9, v62
	global_load_lds_dwordx4 v40, s[60:61]
	s_mov_b32 m0, s72
	s_addc_u32 s7, s61, 0
	s_add_i32 s73, s37, 0x4000
	global_load_lds_dwordx4 v44, s[60:61]
	s_mov_b32 m0, s73
	s_add_i32 s74, s37, 0x6000
	global_load_lds_dwordx4 v40, s[6:7]
	s_mov_b32 m0, s74
	v_mov_b32_e32 v43, 0
	global_load_lds_dwordx4 v44, s[6:7]
	v_mov_b32_e32 v47, v43
	v_mov_b32_e32 v41, v43
	v_mov_b32_e32 v45, v43
	v_lshl_add_u64 v[6:7], s[62:63], 0, v[42:43]
	v_lshl_add_u64 v[4:5], s[62:63], 0, v[46:47]
	v_lshl_add_u64 v[2:3], s[60:61], 0, v[40:41]
	s_cmp_lg_u32 s4, 1
	v_lshl_add_u64 v[0:1], s[60:61], 0, v[44:45]
	s_cbranch_scc1 .Lpp1_299
	s_barrier
.Lpp1_299:
	s_lshl_b32 s0, s0, 5
	s_and_b32 s18, s0, 0x60
	s_mov_b64 s[0:1], 0x80
	s_add_i32 m0, s37, 0x18000
	v_lshl_add_u64 v[6:7], v[6:7], 0, s[0:1]
	s_lshl_b32 s5, s4, 13
	s_lshl_b32 s19, s18, 7
	s_waitcnt vmcnt(2)
	s_and_saveexec_b64 s[98:99], s[12:13]
	s_cbranch_execz .Lpp1_nl
	v_cmp_eq_u32_e32 vcc, 31, v251
	s_cbranch_vccz .Lpp1_nl
	buffer_wbl2 sc1
	s_waitcnt vmcnt(0)
	v_mov_b32_e32 v253, 0x8300
	global_atomic_add v253, v252, s[54:55]
.Lpp1_nl:
	s_or_b64 exec, exec, s[98:99]
	s_barrier
	global_load_lds_dwordx4 v[6:7], off
	v_lshl_add_u64 v[4:5], v[4:5], 0, s[0:1]
	s_add_i32 m0, s37, 0x1a000
	s_add_i32 s75, s37, 0x8000
	s_add_i32 s76, s37, 0xa000
	global_load_lds_dwordx4 v[4:5], off
	v_lshl_add_u64 v[2:3], v[2:3], 0, s[0:1]
	s_mov_b32 m0, s75
	s_add_u32 s6, s62, 0x10080
	global_load_lds_dwordx4 v[2:3], off
	v_lshl_add_u64 v[0:1], v[0:1], 0, s[0:1]
	s_mov_b32 m0, s76
	s_addc_u32 s7, s63, 0
	global_load_lds_dwordx4 v[0:1], off
	s_add_i32 m0, s37, 0x1c000
	v_lshl_add_u64 v[0:1], s[6:7], 0, v[42:43]
	global_load_lds_dwordx4 v[0:1], off
	v_lshl_add_u64 v[0:1], s[6:7], 0, v[46:47]
	s_add_i32 m0, s37, 0x1e000
	v_lshlrev_b32_e32 v2, 2, v149
	global_load_lds_dwordx4 v[0:1], off
	v_lshlrev_b32_e32 v0, 1, v148
	v_lshl_or_b32 v1, v149, 6, v0
	v_and_b32_e32 v2, 32, v2
	v_or_b32_e32 v0, v0, v60
	s_waitcnt vmcnt(6)
	v_bitop3_b32 v1, v1, s5, v2 bitop3:0xde
	v_bitop3_b32 v68, s19, v0, v61 bitop3:0xf6
	s_add_i32 s83, 0, 0x10000
	s_add_i32 s80, 0, 0x14000
	v_lshl_or_b32 v67, s4, 6, v149
	s_ashr_i32 s77, s34, 31
	s_mov_b32 s78, s34
	v_or_b32_e32 v69, s18, v148
	s_add_i32 s79, s2, s34
	v_mov_b64_e32 v[48:49], 0x200
	v_mov_b64_e32 v[50:51], 0x1ff
	v_add_u32_e32 v70, s83, v68
	v_add_u32_e32 v71, s80, v68
	v_add_u32_e32 v72, 0, v1
	s_add_i32 s81, s37, 0xc000
	s_add_i32 s82, s37, 0xe000
	s_mov_b64 s[6:7], 0x100
	s_mov_b64 s[18:19], 0x180
	s_add_i32 s83, s83, s69
	s_mov_b64 s[22:23], s[2:3]
	s_add_u32 s22, s22, 0x100
	s_barrier
	s_branch .Lpp1_302

; __device__ __forceinline__ unsigned xb_ld(unsigned* p)              { return __hip_atomic_load(p, __ATOMIC_RELAXED, __HIP_MEMORY_SCOPE_AGENT); }
; __device__ __forceinline__ unsigned xb_add(unsigned* p, unsigned v) { return __hip_atomic_fetch_add(p, v, __ATOMIC_RELAXED, __HIP_MEMORY_SCOPE_AGENT); }
; #define XB_SPIN(cond, bar) do { unsigned _sp = 0; while (cond) { __builtin_amdgcn_s_sleep(1); \
;     if ((++_sp & 255u) == 0u) { if (xb_ld(&(bar)[XB_TMO])) break; if (_sp > XB_SPIN_CAP) { atomicAdd(&(bar)[XB_TMO], 1u); break; } } } } while (0)
; __device__ __forceinline__ void xcd_barrier(const XcdBarrier& b) {
;     asm volatile("s_waitcnt vmcnt(0)" ::: "memory");
;     __syncthreads();
;     if (threadIdx.x == 0) {
;         unsigned* bar = b.bar;
;         __builtin_amdgcn_s_waitcnt(0);
;         unsigned nloc = b.st[0], nx = b.st[1];
;         if (nloc == 0u) { xcd_barrier_complete(bar, b.x, nloc, nx); b.st[0] = nloc; b.st[1] = nx; }
;         const unsigned old = xb_add(&bar[XB_XSUB(b.x)], 1u);
;         const unsigned gen = old / nloc;
;         if (old + 1u == (gen + 1u) * nloc) {
;             __builtin_amdgcn_fence(__ATOMIC_RELEASE, "agent");
;             asm volatile("s_waitcnt vmcnt(0)" ::: "memory");
;             const unsigned og = xb_add(&bar[XB_TOP], 1u);
;             const unsigned tg = og / nx;
;             if (og + 1u == (tg + 1u) * nx) xb_add(&bar[XB_TOPGEN], 1u);
;             else XB_SPIN(xb_ld(&bar[XB_TOPGEN]) == tg, bar);
;             __builtin_amdgcn_fence(__ATOMIC_ACQUIRE, "agent");
;             xb_add(&bar[XB_XGEN(b.x)], 1u);
;             asm volatile("s_waitcnt vmcnt(0)" ::: "memory");
;         } else {
;             XB_SPIN(xb_ld(&bar[XB_XGEN(b.x)]) == gen, bar);
;             __builtin_amdgcn_fence(__ATOMIC_ACQUIRE, "agent");
;             asm volatile("s_waitcnt vmcnt(0)" ::: "memory");
;         }
;     }
;     __syncthreads();
; }
.Lpp1_exit:
	s_mov_b64 s[0:1], s[100:101]
	s_add_u32 s24, s40, 0x2000000
	s_addc_u32 s25, s41, 0
	s_add_u32 s22, s40, 0x2800000
	s_addc_u32 s23, s41, 0
	s_and_saveexec_b64 s[4:5], s[12:13]
	s_cbranch_execz .LBB0_729
	v_mov_b32_e32 v253, 0x8300
	s_mov_b32 s99, 0
